# prep transposes deal retuned (A 780, B 1860, C 3120 items)
# speedup vs baseline: 1.0031x; 1.0022x over previous
.LBB0_87:
	s_and_b64 s[0:1], s[0:1], s[8:9]
	s_movk_i32 s2, 0x700
	s_and_b64 s[0:1], s[0:1], exec
	s_cselect_b32 s8, s2, 0x1680
	v_readlane_b32 s0, v251, 46
	s_cmpk_lt_i32 s63, 0x80
	s_cbranch_scc1 .Ldeal_ab
	s_lshl_b32 s0, s0, 7
	s_add_i32 s0, s0, s63
	s_add_i32 s6, s0, 0xffffff80
	s_movk_i32 s7, 0x400
	s_movk_i32 s8, 0xc30
	s_branch .Ldeal_done
.Ldeal_ab:
	s_lshl_b32 s0, s0, 6
	s_add_i32 s0, s0, s63
	s_movk_i32 s7, 0x200
	s_cmpk_lt_i32 s63, 0x40
	s_cbranch_scc1 .Ldeal_a
	s_add_i32 s6, s0, 0xbf0
	s_movk_i32 s8, 0x1374
	s_branch .Ldeal_done
.Ldeal_a:
	s_add_i32 s6, s0, 0x1374
	s_movk_i32 s8, 0x1680
